# v23 + grid barrier: XCD leader releases local workgroups before its own L1 invalidate
# speedup vs baseline: 1.0099x; 1.0012x over previous
.LBB0_78:
	s_or_b64 exec, exec, s[8:9]
	s_mov_b64 s[8:9], exec
	v_mbcnt_lo_u32_b32 v2, s8, 0
	v_mbcnt_hi_u32_b32 v2, s9, v2
	v_cmp_eq_u32_e32 vcc, 0, v2
	s_waitcnt vmcnt(0)
	s_and_saveexec_b64 s[10:11], vcc
	s_cbranch_execz .LBB0_80
	s_bcnt1_i32_b64 s0, s[8:9]
	v_mov_b32_e32 v2, 0x2000
	v_mov_b32_e32 v3, s0
	global_atomic_add v2, v3, s[6:7] offset:1024
.LBB0_80:
	s_or_b64 exec, exec, s[10:11]
	buffer_inv sc1
	s_waitcnt vmcnt(0)

.LBB0_483:
	s_or_b64 exec, exec, s[6:7]
	s_mov_b64 s[6:7], exec
	v_mbcnt_lo_u32_b32 v2, s6, 0
	v_mbcnt_hi_u32_b32 v2, s7, v2
	v_cmp_eq_u32_e32 vcc, 0, v2
	s_waitcnt vmcnt(0)
	s_and_saveexec_b64 s[8:9], vcc
	s_cbranch_execz .LBB0_485
	s_bcnt1_i32_b64 s0, s[6:7]
	v_mov_b32_e32 v2, 0x2000
	v_mov_b32_e32 v3, s0
	global_atomic_add v2, v3, s[4:5] offset:1024
.LBB0_485:
	s_or_b64 exec, exec, s[8:9]
	buffer_inv sc1
	s_waitcnt vmcnt(0)

.LBB0_573:
	s_or_b64 exec, exec, s[8:9]
	s_mov_b64 s[8:9], exec
	v_mbcnt_lo_u32_b32 v2, s8, 0
	v_mbcnt_hi_u32_b32 v2, s9, v2
	v_cmp_eq_u32_e32 vcc, 0, v2
	s_waitcnt vmcnt(0)
	s_and_saveexec_b64 s[10:11], vcc
	s_cbranch_execz .LBB0_575
	s_bcnt1_i32_b64 s0, s[8:9]
	v_mov_b32_e32 v2, 0x2000
	v_mov_b32_e32 v3, s0
	global_atomic_add v2, v3, s[4:5] offset:1024

.LBB0_1772:
	s_or_b64 exec, exec, s[6:7]
	s_mov_b64 s[6:7], exec
	v_mbcnt_lo_u32_b32 v2, s6, 0
	v_mbcnt_hi_u32_b32 v2, s7, v2
	v_cmp_eq_u32_e32 vcc, 0, v2
	s_waitcnt vmcnt(0)
	s_and_saveexec_b64 s[10:11], vcc
	s_cbranch_execz .LBB0_1774
	s_bcnt1_i32_b64 s0, s[6:7]
	v_mov_b32_e32 v2, 0x2000
	v_mov_b32_e32 v3, s0
	global_atomic_add v2, v3, s[4:5] offset:1024
